# grid barrier: waiting workgroups issue the L1 invalidate before polling for the release (on top of the conv_weights version)
# speedup vs baseline: 1.0076x; 1.0076x over previous
; __device__ __forceinline__ unsigned xb_ld(unsigned* p)              { return __hip_atomic_load(p, __ATOMIC_RELAXED, __HIP_MEMORY_SCOPE_AGENT); }
; __device__ __forceinline__ unsigned xb_add(unsigned* p, unsigned v) { return __hip_atomic_fetch_add(p, v, __ATOMIC_RELAXED, __HIP_MEMORY_SCOPE_AGENT); }
; #define XB_SPIN(cond, bar) do { unsigned _sp = 0; while (cond) { __builtin_amdgcn_s_sleep(1); \
;     if ((++_sp & 255u) == 0u) { if (xb_ld(&(bar)[XB_TMO])) break; if (_sp > XB_SPIN_CAP) { atomicAdd(&(bar)[XB_TMO], 1u); break; } } } } while (0)
; __device__ __forceinline__ void xcd_barrier(const XcdBarrier& b) {
;     ...
;         const unsigned old = xb_add(&bar[XB_XSUB(b.x)], 1u);
;         const unsigned gen = old / nloc;
;         if (old + 1u == (gen + 1u) * nloc) {
;             __builtin_amdgcn_fence(__ATOMIC_RELEASE, "agent");
;             asm volatile("s_waitcnt vmcnt(0)" ::: "memory");
;             const unsigned og = xb_add(&bar[XB_TOP], 1u);
;             const unsigned tg = og / nx;
;             if (og + 1u == (tg + 1u) * nx) xb_add(&bar[XB_TOPGEN], 1u);
;             else XB_SPIN(xb_ld(&bar[XB_TOPGEN]) == tg, bar);
;             __builtin_amdgcn_fence(__ATOMIC_ACQUIRE, "agent");
;             xb_add(&bar[XB_XGEN(b.x)], 1u);
;             asm volatile("s_waitcnt vmcnt(0)" ::: "memory");
;         } else {
;             XB_SPIN(xb_ld(&bar[XB_XGEN(b.x)]) == gen, bar);
;             __builtin_amdgcn_fence(__ATOMIC_ACQUIRE, "agent");
;             asm volatile("s_waitcnt vmcnt(0)" ::: "memory");
.LBB0_253:
	s_or_b64 exec, exec, s[6:7]
	v_cvt_f32_u32_e32 v5, v3
	s_waitcnt vmcnt(0)
	v_readfirstlane_b32 s6, v4
	v_sub_u32_e32 v4, 0, v3
	v_rcp_iflag_f32_e32 v5, v5
	v_add_u32_e32 v6, s6, v0
	v_mul_f32_e32 v5, 0x4f7ffffe, v5
	v_cvt_u32_f32_e32 v5, v5
	v_mul_lo_u32 v0, v4, v5
	v_mul_hi_u32 v0, v5, v0
	v_add_u32_e32 v0, v5, v0
	v_mul_hi_u32 v0, v6, v0
	v_mul_lo_u32 v4, v0, v3
	v_sub_u32_e32 v4, v6, v4
	v_add_u32_e32 v5, 1, v0
	v_cmp_ge_u32_e32 vcc, v4, v3
	s_nop 1
	v_cndmask_b32_e32 v0, v0, v5, vcc
	v_sub_u32_e32 v5, v4, v3
	v_cndmask_b32_e32 v4, v4, v5, vcc
	v_add_u32_e32 v5, 1, v0
	v_cmp_ge_u32_e32 vcc, v4, v3
	v_add_u32_e32 v4, 1, v6
	s_nop 0
	v_cndmask_b32_e32 v0, v0, v5, vcc
	v_mul_lo_u32 v5, v3, v0
	v_add_u32_e32 v3, v5, v3
	v_cmp_ne_u32_e32 vcc, v4, v3
	s_and_saveexec_b64 s[6:7], vcc
	s_xor_b64 s[6:7], exec, s[6:7]
	s_cbranch_execz .LBB0_267
	v_readlane_b32 s8, v253, 9
	v_readlane_b32 s9, v253, 10
	s_waitcnt lgkmcnt(0)
	s_nop 3
	buffer_inv sc1
	global_load_dword v2, v1, s[8:9] sc1
	s_waitcnt vmcnt(0)
	v_cmp_eq_u32_e32 vcc, v2, v0
	s_and_saveexec_b64 s[8:9], vcc
	s_cbranch_execz .LBB0_266
	s_mov_b32 s20, 1
	s_mov_b64 s[10:11], 0
	s_branch .LBB0_257

; __device__ __forceinline__ unsigned xb_ld(unsigned* p)              { return __hip_atomic_load(p, __ATOMIC_RELAXED, __HIP_MEMORY_SCOPE_AGENT); }
; #define XB_SPIN(cond, bar) do { unsigned _sp = 0; while (cond) { __builtin_amdgcn_s_sleep(1); \
;     if ((++_sp & 255u) == 0u) { if (xb_ld(&(bar)[XB_TMO])) break; if (_sp > XB_SPIN_CAP) { atomicAdd(&(bar)[XB_TMO], 1u); break; } } } } while (0)
; __device__ __forceinline__ void xcd_barrier(const XcdBarrier& b) {
;     ...
;             XB_SPIN(xb_ld(&bar[XB_XGEN(b.x)]) == gen, bar);
;             __builtin_amdgcn_fence(__ATOMIC_ACQUIRE, "agent");
;             asm volatile("s_waitcnt vmcnt(0)" ::: "memory");
.LBB0_266:
	s_or_b64 exec, exec, s[8:9]
	s_waitcnt vmcnt(0)
	s_nop 0
	s_waitcnt vmcnt(0)

; __device__ __forceinline__ unsigned xb_ld(unsigned* p)              { return __hip_atomic_load(p, __ATOMIC_RELAXED, __HIP_MEMORY_SCOPE_AGENT); }
; __device__ __forceinline__ unsigned xb_add(unsigned* p, unsigned v) { return __hip_atomic_fetch_add(p, v, __ATOMIC_RELAXED, __HIP_MEMORY_SCOPE_AGENT); }
; #define XB_SPIN(cond, bar) do { unsigned _sp = 0; while (cond) { __builtin_amdgcn_s_sleep(1); \
;     if ((++_sp & 255u) == 0u) { if (xb_ld(&(bar)[XB_TMO])) break; if (_sp > XB_SPIN_CAP) { atomicAdd(&(bar)[XB_TMO], 1u); break; } } } } while (0)
; __device__ __forceinline__ void xcd_barrier(const XcdBarrier& b) {
;     ...
;         const unsigned old = xb_add(&bar[XB_XSUB(b.x)], 1u);
;         const unsigned gen = old / nloc;
;         if (old + 1u == (gen + 1u) * nloc) {
;             __builtin_amdgcn_fence(__ATOMIC_RELEASE, "agent");
;             asm volatile("s_waitcnt vmcnt(0)" ::: "memory");
;             const unsigned og = xb_add(&bar[XB_TOP], 1u);
;             const unsigned tg = og / nx;
;             if (og + 1u == (tg + 1u) * nx) xb_add(&bar[XB_TOPGEN], 1u);
;             else XB_SPIN(xb_ld(&bar[XB_TOPGEN]) == tg, bar);
;             __builtin_amdgcn_fence(__ATOMIC_ACQUIRE, "agent");
;             xb_add(&bar[XB_XGEN(b.x)], 1u);
;             asm volatile("s_waitcnt vmcnt(0)" ::: "memory");
;         } else {
;             XB_SPIN(xb_ld(&bar[XB_XGEN(b.x)]) == gen, bar);
;             __builtin_amdgcn_fence(__ATOMIC_ACQUIRE, "agent");
;             asm volatile("s_waitcnt vmcnt(0)" ::: "memory");
.LBB0_1593:
	s_or_b64 exec, exec, s[8:9]
	v_cvt_f32_u32_e32 v5, v3
	s_waitcnt vmcnt(0)
	v_readfirstlane_b32 s8, v4
	v_sub_u32_e32 v4, 0, v3
	v_rcp_iflag_f32_e32 v5, v5
	v_add_u32_e32 v6, s8, v0
	v_mul_f32_e32 v5, 0x4f7ffffe, v5
	v_cvt_u32_f32_e32 v5, v5
	v_mul_lo_u32 v0, v4, v5
	v_mul_hi_u32 v0, v5, v0
	v_add_u32_e32 v0, v5, v0
	v_mul_hi_u32 v0, v6, v0
	v_mul_lo_u32 v4, v0, v3
	v_sub_u32_e32 v4, v6, v4
	v_add_u32_e32 v5, 1, v0
	v_cmp_ge_u32_e32 vcc, v4, v3
	s_nop 1
	v_cndmask_b32_e32 v0, v0, v5, vcc
	v_sub_u32_e32 v5, v4, v3
	v_cndmask_b32_e32 v4, v4, v5, vcc
	v_add_u32_e32 v5, 1, v0
	v_cmp_ge_u32_e32 vcc, v4, v3
	v_add_u32_e32 v4, 1, v6
	s_nop 0
	v_cndmask_b32_e32 v0, v0, v5, vcc
	v_mul_lo_u32 v5, v3, v0
	v_add_u32_e32 v3, v5, v3
	v_cmp_ne_u32_e32 vcc, v4, v3
	s_and_saveexec_b64 s[8:9], vcc
	s_xor_b64 s[8:9], exec, s[8:9]
	s_cbranch_execz .LBB0_1607
	v_readlane_b32 s10, v253, 9
	v_readlane_b32 s11, v253, 10
	s_waitcnt lgkmcnt(0)
	s_nop 3
	buffer_inv sc1
	global_load_dword v2, v1, s[10:11] sc1
	s_waitcnt vmcnt(0)
	v_cmp_eq_u32_e32 vcc, v2, v0
	s_and_saveexec_b64 s[10:11], vcc
	s_cbranch_execz .LBB0_1606
	s_mov_b32 s22, 1
	s_mov_b64 s[12:13], 0
	s_branch .LBB0_1597

; __device__ __forceinline__ unsigned xb_ld(unsigned* p)              { return __hip_atomic_load(p, __ATOMIC_RELAXED, __HIP_MEMORY_SCOPE_AGENT); }
; #define XB_SPIN(cond, bar) do { unsigned _sp = 0; while (cond) { __builtin_amdgcn_s_sleep(1); \
;     if ((++_sp & 255u) == 0u) { if (xb_ld(&(bar)[XB_TMO])) break; if (_sp > XB_SPIN_CAP) { atomicAdd(&(bar)[XB_TMO], 1u); break; } } } } while (0)
; __device__ __forceinline__ void xcd_barrier(const XcdBarrier& b) {
;     ...
;             XB_SPIN(xb_ld(&bar[XB_XGEN(b.x)]) == gen, bar);
;             __builtin_amdgcn_fence(__ATOMIC_ACQUIRE, "agent");
;             asm volatile("s_waitcnt vmcnt(0)" ::: "memory");
.LBB0_1606:
	s_or_b64 exec, exec, s[10:11]
	s_waitcnt vmcnt(0)
	s_nop 0
	s_waitcnt vmcnt(0)
